# E score-GEMM tile remap: co-resident blocks b and b+256 take the same 256-row A tile with adjacent key tiles (swap bits 3 and 8 of the tile index)
# baseline (speedup 1.0000x reference)
; __global__ void __launch_bounds__(256, 2) fwd_kernel(P p) {
;     ...
;       bf16_t* SCB = (bf16_t*)(ws + OFF_R + R_SC_BYTES);
;       for (int rep = 0; rep < REP_E; ++rep)
;       for (int it = blockIdx.x; it < 64 * 16; it += G) {
;         const int tm = (it & 7) * 8 + ((it >> 3) >> 4), tn = (it >> 3) & 15;
;         gemm_tile_bf16<8, true>((const bf16_t*)(ws + OFF_AO + (32ull << 20)) + (size_t)tm * 256 * 512, 512,
;                        (const bf16_t*)(ws + OFF_WPQ) + ((size_t)layer * 2048 + tn * 128) * 512, 512, 512,
;                        SCB + (size_t)tm * 256 * 2048 + tn * 128, 2048, smem);
;       }
.LBB0_941:
	s_or_b64 exec, exec, s[0:1]
	v_readlane_b32 s0, v255, 44
	s_add_u32 s42, s12, 0x1da84000
	v_readlane_b32 s1, v255, 45
	s_addc_u32 s43, s13, 0
	s_andn2_b64 vcc, exec, s[0:1]
	s_waitcnt lgkmcnt(0)
	s_barrier
	s_cbranch_vccnz .LBB0_946
	s_lshl_b64 s[0:1], s[54:55], 21
	s_add_u32 s0, s12, s0
	s_addc_u32 s1, s13, s1
	s_add_u32 s16, s0, 0x2884000
	s_addc_u32 s17, s1, 0
	v_readlane_b32 s0, v255, 58
	v_readlane_b32 s1, v255, 59
	s_add_u32 s0, s0, s14
	v_readlane_b32 s6, v255, 53
	s_addc_u32 s1, s1, s15
	v_readlane_b32 s14, v255, 51
	v_readlane_b32 s15, v255, 48
	s_mov_b32 s18, s6
	s_bfe_u32 s6, s18, 0x10003
	s_bfe_u32 s8, s18, 0x10008
	s_andn2_b32 s18, s18, 0x108
	s_lshl_b32 s6, s6, 8
	s_lshl_b32 s8, s8, 3
	s_or_b32 s18, s18, s6
	s_or_b32 s18, s18, s8
	s_lshl_b32 s14, s18, 4
	s_lshl_b32 s15, s18, 3
	v_readlane_b32 s7, v255, 54
